# grid barrier: acquire invalidate issued behind the arrival atomic instead of after the release
# speedup vs baseline: 1.0408x; 1.0032x over previous
; __device__ __forceinline__ unsigned xb_add(unsigned* p, unsigned v) { return __hip_atomic_fetch_add(p, v, __ATOMIC_RELAXED, __HIP_MEMORY_SCOPE_AGENT); }
; __device__ __forceinline__ void xcd_barrier(const XcdBarrier& b) {
;     ...
;         const unsigned old = xb_add(&bar[XB_XSUB(b.x)], 1u);
;         const unsigned gen = old / nloc;
;         if (old + 1u == (gen + 1u) * nloc) {
;             __builtin_amdgcn_fence(__ATOMIC_RELEASE, "agent");
;             asm volatile("s_waitcnt vmcnt(0)" ::: "memory");
;             const unsigned og = xb_add(&bar[XB_TOP], 1u);
;             const unsigned tg = og / nx;
.LBB0_163:
	s_mov_b64 s[6:7], exec
	s_lshl_b32 s4, s74, 8
	v_mbcnt_lo_u32_b32 v2, s6, 0
	s_add_u32 s4, s72, s4
	v_mbcnt_hi_u32_b32 v2, s7, v2
	s_addc_u32 s5, s73, 0
	v_cmp_eq_u32_e32 vcc, 0, v2
	s_and_saveexec_b64 s[8:9], vcc
	s_cbranch_execz .LBB0_165
	s_bcnt1_i32_b64 s6, s[6:7]
	v_mov_b32_e32 v4, 0x1000
	v_mov_b32_e32 v5, s6
	global_atomic_add v4, v4, v5, s[4:5] offset:1024 sc0
	buffer_inv sc1

; __device__ __forceinline__ unsigned xb_ld(unsigned* p)              { return __hip_atomic_load(p, __ATOMIC_RELAXED, __HIP_MEMORY_SCOPE_AGENT); }
; #define XB_SPIN(cond, bar) do { unsigned _sp = 0; while (cond) { __builtin_amdgcn_s_sleep(1); \
;     if ((++_sp & 255u) == 0u) { if (xb_ld(&(bar)[XB_TMO])) break; if (_sp > XB_SPIN_CAP) { atomicAdd(&(bar)[XB_TMO], 1u); break; } } } } while (0)
; __device__ __forceinline__ void xcd_barrier(const XcdBarrier& b) {
;     ...
;         } else {
;             XB_SPIN(xb_ld(&bar[XB_XGEN(b.x)]) == gen, bar);
;             __builtin_amdgcn_fence(__ATOMIC_ACQUIRE, "agent");
;             asm volatile("s_waitcnt vmcnt(0)" ::: "memory");
.LBB0_178:
	s_or_b64 exec, exec, s[8:9]
	s_waitcnt vmcnt(0)
	s_waitcnt vmcnt(0)

; __device__ __forceinline__ unsigned xb_ld(unsigned* p)              { return __hip_atomic_load(p, __ATOMIC_RELAXED, __HIP_MEMORY_SCOPE_AGENT); }
; __device__ __forceinline__ unsigned xb_add(unsigned* p, unsigned v) { return __hip_atomic_fetch_add(p, v, __ATOMIC_RELAXED, __HIP_MEMORY_SCOPE_AGENT); }
; #define XB_SPIN(cond, bar) do { unsigned _sp = 0; while (cond) { __builtin_amdgcn_s_sleep(1); \
;     if ((++_sp & 255u) == 0u) { if (xb_ld(&(bar)[XB_TMO])) break; if (_sp > XB_SPIN_CAP) { atomicAdd(&(bar)[XB_TMO], 1u); break; } } } } while (0)
; __device__ __forceinline__ void xcd_barrier(const XcdBarrier& b) {
;     ...
;             if (og + 1u == (tg + 1u) * nx) xb_add(&bar[XB_TOPGEN], 1u);
;             else XB_SPIN(xb_ld(&bar[XB_TOPGEN]) == tg, bar);
;             __builtin_amdgcn_fence(__ATOMIC_ACQUIRE, "agent");
;             xb_add(&bar[XB_XGEN(b.x)], 1u);
;             asm volatile("s_waitcnt vmcnt(0)" ::: "memory");
.LBB0_196:
	s_or_b64 exec, exec, s[6:7]
	s_mov_b64 s[6:7], exec
	v_mbcnt_lo_u32_b32 v1, s6, 0
	v_mbcnt_hi_u32_b32 v1, s7, v1
	v_cmp_eq_u32_e32 vcc, 0, v1
	s_waitcnt vmcnt(0)
	s_and_saveexec_b64 s[8:9], vcc
	s_cbranch_execz .LBB0_198
	s_bcnt1_i32_b64 s6, s[6:7]
	v_mov_b32_e32 v1, 0x2000
	v_mov_b32_e32 v2, s6
	global_atomic_add v1, v2, s[4:5] offset:1024

; __device__ __forceinline__ unsigned xb_add(unsigned* p, unsigned v) { return __hip_atomic_fetch_add(p, v, __ATOMIC_RELAXED, __HIP_MEMORY_SCOPE_AGENT); }
; __device__ __forceinline__ void xcd_barrier(const XcdBarrier& b) {
;     ...
;         const unsigned old = xb_add(&bar[XB_XSUB(b.x)], 1u);
;         const unsigned gen = old / nloc;
;         if (old + 1u == (gen + 1u) * nloc) {
;             __builtin_amdgcn_fence(__ATOMIC_RELEASE, "agent");
;             asm volatile("s_waitcnt vmcnt(0)" ::: "memory");
;             const unsigned og = xb_add(&bar[XB_TOP], 1u);
;             const unsigned tg = og / nx;
.LBB0_707:
	s_mov_b64 s[6:7], exec
	v_mbcnt_lo_u32_b32 v3, s6, 0
	v_mbcnt_hi_u32_b32 v3, s7, v3
	v_cmp_eq_u32_e32 vcc, 0, v3
	s_and_saveexec_b64 s[4:5], vcc
	s_cbranch_execz .LBB0_709
	s_bcnt1_i32_b64 s6, s[6:7]
	v_mov_b32_e32 v5, s6
	v_readlane_b32 s6, v252, 25
	v_readlane_b32 s7, v252, 26
	s_nop 4
	global_atomic_add v5, v195, v5, s[6:7] sc0
	buffer_inv sc1

; __device__ __forceinline__ unsigned xb_ld(unsigned* p)              { return __hip_atomic_load(p, __ATOMIC_RELAXED, __HIP_MEMORY_SCOPE_AGENT); }
; #define XB_SPIN(cond, bar) do { unsigned _sp = 0; while (cond) { __builtin_amdgcn_s_sleep(1); \
;     if ((++_sp & 255u) == 0u) { if (xb_ld(&(bar)[XB_TMO])) break; if (_sp > XB_SPIN_CAP) { atomicAdd(&(bar)[XB_TMO], 1u); break; } } } } while (0)
; __device__ __forceinline__ void xcd_barrier(const XcdBarrier& b) {
;     ...
;         } else {
;             XB_SPIN(xb_ld(&bar[XB_XGEN(b.x)]) == gen, bar);
;             __builtin_amdgcn_fence(__ATOMIC_ACQUIRE, "agent");
;             asm volatile("s_waitcnt vmcnt(0)" ::: "memory");
.LBB0_722:
	s_or_b64 exec, exec, s[6:7]
	s_waitcnt vmcnt(0)
	s_waitcnt vmcnt(0)

; __device__ __forceinline__ unsigned xb_ld(unsigned* p)              { return __hip_atomic_load(p, __ATOMIC_RELAXED, __HIP_MEMORY_SCOPE_AGENT); }
; __device__ __forceinline__ unsigned xb_add(unsigned* p, unsigned v) { return __hip_atomic_fetch_add(p, v, __ATOMIC_RELAXED, __HIP_MEMORY_SCOPE_AGENT); }
; #define XB_SPIN(cond, bar) do { unsigned _sp = 0; while (cond) { __builtin_amdgcn_s_sleep(1); \
;     if ((++_sp & 255u) == 0u) { if (xb_ld(&(bar)[XB_TMO])) break; if (_sp > XB_SPIN_CAP) { atomicAdd(&(bar)[XB_TMO], 1u); break; } } } } while (0)
; __device__ __forceinline__ void xcd_barrier(const XcdBarrier& b) {
;     ...
;             if (og + 1u == (tg + 1u) * nx) xb_add(&bar[XB_TOPGEN], 1u);
;             else XB_SPIN(xb_ld(&bar[XB_TOPGEN]) == tg, bar);
;             __builtin_amdgcn_fence(__ATOMIC_ACQUIRE, "agent");
;             xb_add(&bar[XB_XGEN(b.x)], 1u);
;             asm volatile("s_waitcnt vmcnt(0)" ::: "memory");
.LBB0_740:
	s_or_b64 exec, exec, s[4:5]
	s_mov_b64 s[4:5], exec
	v_mbcnt_lo_u32_b32 v2, s4, 0
	v_mbcnt_hi_u32_b32 v2, s5, v2
	v_cmp_eq_u32_e32 vcc, 0, v2
	s_waitcnt vmcnt(0)
	s_and_saveexec_b64 s[6:7], vcc
	s_cbranch_execz .LBB0_742
	s_bcnt1_i32_b64 s4, s[4:5]
	v_mov_b32_e32 v2, s4
	v_readlane_b32 s4, v252, 27
	v_readlane_b32 s5, v252, 28
	s_nop 4
	global_atomic_add v195, v2, s[4:5]

; __device__ __forceinline__ unsigned xb_ld(unsigned* p)              { return __hip_atomic_load(p, __ATOMIC_RELAXED, __HIP_MEMORY_SCOPE_AGENT); }
; __device__ __forceinline__ unsigned xb_add(unsigned* p, unsigned v) { return __hip_atomic_fetch_add(p, v, __ATOMIC_RELAXED, __HIP_MEMORY_SCOPE_AGENT); }
; #define XB_SPIN(cond, bar) do { unsigned _sp = 0; while (cond) { __builtin_amdgcn_s_sleep(1); \
;     if ((++_sp & 255u) == 0u) { if (xb_ld(&(bar)[XB_TMO])) break; if (_sp > XB_SPIN_CAP) { atomicAdd(&(bar)[XB_TMO], 1u); break; } } } } while (0)
; __device__ __forceinline__ void xcd_barrier(const XcdBarrier& b) {
;     ...
;             if (og + 1u == (tg + 1u) * nx) xb_add(&bar[XB_TOPGEN], 1u);
;             else XB_SPIN(xb_ld(&bar[XB_TOPGEN]) == tg, bar);
;             __builtin_amdgcn_fence(__ATOMIC_ACQUIRE, "agent");
;             xb_add(&bar[XB_XGEN(b.x)], 1u);
;             asm volatile("s_waitcnt vmcnt(0)" ::: "memory");
.LBB0_2587:
	s_or_b64 exec, exec, s[4:5]
	s_mov_b64 s[4:5], exec
	v_mbcnt_lo_u32_b32 v2, s4, 0
	v_mbcnt_hi_u32_b32 v2, s5, v2
	v_cmp_eq_u32_e32 vcc, 0, v2
	s_waitcnt vmcnt(0)
	s_and_saveexec_b64 s[6:7], vcc
	s_cbranch_execnz .LBB0_2588
	s_getpc_b64 s[98:99]
